# raised wave priority while a workgroup runs a MoBA item
# speedup vs baseline: 1.0340x; 1.0027x over previous
.LBB0_330:
	s_setprio 0
	s_or_b64 exec, exec, s[82:83]
	s_and_b64 s[2:3], exec, s[2:3]
	s_or_b64 s[78:79], s[2:3], s[78:79]
	s_andn2_b64 exec, exec, s[78:79]
	s_cbranch_execz .LBB0_436

.LBB0_335:
	s_or_b64 exec, exec, s[2:3]
	v_mov_b32_e32 v199, v201
	s_waitcnt lgkmcnt(0)
	s_barrier
	flat_load_dword v8, v[198:199] sc0 sc1
	s_waitcnt vmcnt(0)
	s_mov_b64 s[2:3], -1
	s_waitcnt lgkmcnt(0)
	v_cmp_gt_i32_e32 vcc, 64, v8
	s_and_saveexec_b64 s[82:83], vcc
	s_cbranch_execz .LBB0_330
	s_setprio 2
	v_ashrrev_i32_e32 v33, 2, v8
	v_sub_u32_e32 v7, 15, v33
	v_mov_b32_e32 v3, v197
	v_lshlrev_b32_e32 v0, 5, v8
	v_readlane_b32 s2, v249, 37
	v_lshlrev_b32_e32 v9, 6, v7
	s_nop 0
	v_and_or_b32 v32, v0, 64, s2
	v_cmp_lt_i32_e32 vcc, v3, v9
	s_barrier
	s_and_saveexec_b64 s[2:3], vcc
	s_cbranch_execz .LBB0_344
	v_readlane_b32 s8, v249, 38
	v_lshlrev_b32_e32 v0, 2, v32
	v_mov_b32_e32 v1, v2
	v_readlane_b32 s9, v249, 39
	v_and_b32_e32 v4, 63, v3
	v_lshlrev_b32_e32 v4, 2, v4
	v_lshl_add_u64 v[0:1], s[8:9], 0, v[0:1]
	v_mov_b32_e32 v5, v2
	v_lshl_add_u64 v[0:1], v[0:1], 0, v[4:5]
	v_add_u32_e32 v5, 0x100, v3
	v_max_i32_e32 v4, v9, v5
	v_xad_u32 v12, v3, -1, v4
	s_movk_i32 s8, 0xff
	v_cmp_lt_u32_e32 vcc, s8, v12
	s_mov_b64 s[10:11], -1
	v_mov_b32_e32 v4, v3
	s_and_saveexec_b64 s[8:9], vcc
	s_cbranch_execz .LBB0_341
	v_lshrrev_b32_e32 v4, 8, v12
	v_add_u32_e32 v12, 1, v4
	v_and_b32_e32 v13, 0x1fffffe, v12
	v_mov_b32_e32 v4, v3
	v_lshl_add_u32 v15, v3, 2, v210
	s_mov_b64 s[10:11], 0
	v_mov_b32_e32 v16, v13
	v_readlane_b32 s15, v248, 5
